# v101 + conv FMA-loop address increments via one SGPR-pair add + P9 and P0 cross-lane reductions via DPP/permlane (stack of individually validated micro changes)
# baseline (speedup 1.0000x reference)
; #define LAS __attribute__((address_space(3)))
; __global__ void __launch_bounds__(NWAVES * 64, 2) mk_fwd(Args args) {
;     ...
;             const int cp = tid & 255, th = tid >> 8;
;             f32x2 w[31];
; #pragma unroll
;             for (int j = 0; j < 31; ++j) w[j] = *(const f32x2*)(conv_w + j * 512 + 2 * cp);
;             const f32x2 cb = *(const f32x2*)(conv_b + 2 * cp);
;             LAS float* yt = (LAS float*)lds;
;             f32x4 lg0 = *(const f32x4*)(ln_g + 4 * lane), lg1 = *(const f32x4*)(ln_g + 256 + 4 * lane), lb0 = *(const f32x4*)(ln_b + 4 * lane), lb1 = *(const f32x4*)(ln_b + 256 + 4 * lane);
;     ...
;             for (int repc = 0; repc < REPC; ++repc)
;             for (int kt = 0, tile = (G == 256) ? 64 * (vcu >> 5) + (vcu & 31) : vcu; tile < T / 64; ++kt, tile = (G == 256) ? ((kt < 2) ? 64 * (vcu >> 5) + 32 * kt + (vcu & 31) : T) : tile + G) {
.LBB0_352:
	s_lshl_b32 s4, s73, 1
	s_andn2_b32 s4, s4, 63
	s_and_b32 s5, s73, 31
	s_or_b32 s4, s4, s5
	s_and_b64 s[6:7], s[50:51], exec
	s_cselect_b32 s6, s4, s73
	s_cmpk_lt_i32 s6, 0x200
	s_cbranch_scc0 .LBB0_361
	v_lshlrev_b32_e32 v0, 1, v200
	v_and_b32_e32 v20, 0x1fe, v0
	v_mov_b32_e32 v80, 0
	v_lshlrev_b32_e32 v0, 2, v20
	v_mov_b32_e32 v1, v80
	v_lshl_add_u64 v[2:3], s[18:19], 0, v[0:1]
	v_add_co_u32_e32 v4, vcc, 0x1000, v2
	v_lshl_add_u64 v[0:1], s[16:17], 0, v[0:1]
	s_nop 0
	v_addc_co_u32_e32 v5, vcc, 0, v3, vcc
	flat_load_dwordx2 v[82:83], v[2:3]
	flat_load_dwordx2 v[84:85], v[2:3] offset:2048
	flat_load_dwordx2 v[86:87], v[4:5]
	flat_load_dwordx2 v[88:89], v[4:5] offset:2048
	v_add_co_u32_e32 v4, vcc, 0x2000, v2
	v_mov_b32_e32 v17, v80
	s_nop 0
	v_addc_co_u32_e32 v5, vcc, 0, v3, vcc
	v_add_co_u32_e32 v6, vcc, 0x3000, v2
	s_ashr_i32 s5, s72, 6
	s_nop 0
	v_addc_co_u32_e32 v7, vcc, 0, v3, vcc
	flat_load_dwordx2 v[90:91], v[4:5]
	flat_load_dwordx2 v[92:93], v[4:5] offset:2048
	flat_load_dwordx2 v[94:95], v[6:7]
	flat_load_dwordx2 v[96:97], v[6:7] offset:2048
	v_add_co_u32_e32 v4, vcc, 0x4000, v2
	s_movk_i32 s7, 0x1000
	s_nop 0
	v_addc_co_u32_e32 v5, vcc, 0, v3, vcc
	v_add_co_u32_e32 v6, vcc, 0x5000, v2
	s_movk_i32 s8, 0x2000
	s_nop 0
	v_addc_co_u32_e32 v7, vcc, 0, v3, vcc
	flat_load_dwordx2 v[98:99], v[4:5]
	s_nop 0
	flat_load_dwordx2 v[100:101], v[4:5] offset:2048
	flat_load_dwordx2 v[102:103], v[6:7]
	flat_load_dwordx2 v[104:105], v[6:7] offset:2048
	v_add_co_u32_e32 v4, vcc, 0x6000, v2
	s_movk_i32 s9, 0x3000
	s_nop 0
	v_addc_co_u32_e32 v5, vcc, 0, v3, vcc
	v_add_co_u32_e32 v6, vcc, 0x7000, v2
	v_mov_b32_e32 v176, 0x358637bd
	s_nop 0
	v_addc_co_u32_e32 v7, vcc, 0, v3, vcc
	flat_load_dwordx2 v[106:107], v[4:5]
	flat_load_dwordx2 v[108:109], v[4:5] offset:2048
	flat_load_dwordx2 v[110:111], v[6:7]
	flat_load_dwordx2 v[112:113], v[6:7] offset:2048
	v_add_co_u32_e32 v4, vcc, 0x8000, v2
	v_mov_b32_e32 v177, 0x260
	s_nop 0
	v_addc_co_u32_e32 v5, vcc, 0, v3, vcc
	v_add_co_u32_e32 v6, vcc, 0x9000, v2
	s_nop 1
	v_addc_co_u32_e32 v7, vcc, 0, v3, vcc
	flat_load_dwordx2 v[114:115], v[4:5]
	flat_load_dwordx2 v[116:117], v[4:5] offset:2048
	flat_load_dwordx2 v[118:119], v[6:7]
	flat_load_dwordx2 v[120:121], v[6:7] offset:2048
	v_add_co_u32_e32 v4, vcc, 0xa000, v2
	s_nop 1
	v_addc_co_u32_e32 v5, vcc, 0, v3, vcc
	v_add_co_u32_e32 v6, vcc, 0xb000, v2
	s_nop 1
	v_addc_co_u32_e32 v7, vcc, 0, v3, vcc
	flat_load_dwordx2 v[122:123], v[4:5]
	flat_load_dwordx2 v[124:125], v[4:5] offset:2048
	flat_load_dwordx2 v[126:127], v[6:7]
	flat_load_dwordx2 v[128:129], v[6:7] offset:2048
	v_add_co_u32_e32 v4, vcc, 0xc000, v2
	s_nop 1
	v_addc_co_u32_e32 v5, vcc, 0, v3, vcc
	v_add_co_u32_e32 v6, vcc, 0xd000, v2
	s_nop 1
	v_addc_co_u32_e32 v7, vcc, 0, v3, vcc
	flat_load_dwordx2 v[130:131], v[4:5]
	flat_load_dwordx2 v[132:133], v[4:5] offset:2048
	flat_load_dwordx2 v[134:135], v[6:7]
	flat_load_dwordx2 v[136:137], v[6:7] offset:2048
	v_add_co_u32_e32 v4, vcc, 0xe000, v2
	s_nop 1
	v_addc_co_u32_e32 v5, vcc, 0, v3, vcc
	v_add_co_u32_e32 v2, vcc, 0xf000, v2
	s_nop 1
	v_addc_co_u32_e32 v3, vcc, 0, v3, vcc
	flat_load_dwordx2 v[138:139], v[4:5]
	flat_load_dwordx2 v[140:141], v[4:5] offset:2048
	flat_load_dwordx2 v[142:143], v[2:3]
	flat_load_dwordx2 v[144:145], v[0:1]
	v_lshlrev_b32_e32 v0, 2, v200
	v_and_b32_e32 v21, 0xfc, v0
	v_lshlrev_b32_e32 v16, 2, v21
	v_lshl_add_u64 v[8:9], s[12:13], 0, v[16:17]
	v_lshl_add_u64 v[18:19], s[14:15], 0, v[16:17]
	flat_load_dwordx4 v[0:3], v[8:9]
	flat_load_dwordx4 v[4:7], v[8:9] offset:1024
	s_nop 0
	flat_load_dwordx4 v[8:11], v[18:19]
	flat_load_dwordx4 v[12:15], v[18:19] offset:1024
	v_lshlrev_b32_e32 v18, 1, v20
	v_mov_b32_e32 v19, v80
	v_lshl_add_u64 v[18:19], s[2:3], 0, v[18:19]
	s_mov_b64 s[14:15], 0x8000000
	v_mbcnt_lo_u32_b32 v17, -1, 0
	v_lshl_add_u64 v[146:147], v[18:19], 0, s[14:15]
	s_or_b32 s15, s4, 32
	s_lshl_b32 s4, s5, 14
	v_mbcnt_hi_u32_b32 v17, -1, v17
	s_add_i32 s4, s4, 0
	v_and_b32_e32 v19, 64, v17
	v_add_u32_e32 v19, 64, v19
	v_add_u32_e32 v168, s4, v16
	v_xor_b32_e32 v16, 1, v17
	v_cmp_lt_i32_e32 vcc, v16, v19
	s_lshl_b32 s14, s5, 3
	s_mov_b64 s[4:5], 0x14000000
	v_cndmask_b32_e32 v16, v17, v16, vcc
	v_lshlrev_b32_e32 v169, 2, v16
	v_xor_b32_e32 v16, 2, v17
	v_cmp_lt_i32_e32 vcc, v16, v19
	v_ashrrev_i32_e32 v18, 3, v200
	v_and_b32_e32 v166, 0xffffffe0, v18
	v_cndmask_b32_e32 v16, v17, v16, vcc
	v_lshlrev_b32_e32 v170, 2, v16
	v_xor_b32_e32 v16, 4, v17
	v_cmp_lt_i32_e32 vcc, v16, v19
	s_mov_b32 s13, 0
	s_movk_i32 s12, 0x5000
	v_cndmask_b32_e32 v16, v17, v16, vcc
	v_lshlrev_b32_e32 v171, 2, v16
	v_xor_b32_e32 v16, 8, v17
	v_cmp_lt_i32_e32 vcc, v16, v19
	v_sub_u32_e32 v167, 0, v166
	s_nop 0
	v_cndmask_b32_e32 v16, v17, v16, vcc
	v_lshlrev_b32_e32 v172, 2, v16
	v_xor_b32_e32 v16, 16, v17
	v_cmp_lt_i32_e32 vcc, v16, v19
	s_nop 1
	v_cndmask_b32_e32 v16, v17, v16, vcc
	v_lshlrev_b32_e32 v173, 2, v16
	v_xor_b32_e32 v16, 32, v17
	v_cmp_lt_i32_e32 vcc, v16, v19
	s_nop 1
	v_cndmask_b32_e32 v16, v17, v16, vcc
	v_lshlrev_b32_e32 v174, 2, v16
	v_lshlrev_b32_e32 v16, 1, v21
	v_mov_b32_e32 v17, v80
	v_lshl_add_u64 v[16:17], s[10:11], 0, v[16:17]
	v_lshl_add_u64 v[148:149], v[16:17], 0, s[4:5]
	v_mov_b32_e32 v16, 2
	v_lshlrev_b32_sdwa v16, v16, v200 dst_sel:DWORD dst_unused:UNUSED_PAD src0_sel:DWORD src1_sel:BYTE_0
	v_mov_b32_e32 v17, v80
	v_lshl_add_u64 v[150:151], s[2:3], 0, v[16:17]
	v_mov_b32_e32 v17, 3
	v_lshlrev_b32_e32 v16, 11, v18
	v_lshlrev_b32_sdwa v17, v17, v200 dst_sel:DWORD dst_unused:UNUSED_PAD src0_sel:DWORD src1_sel:BYTE_0
	s_mov_b32 s2, 0xffff0000
	v_and_or_b32 v16, v16, s2, v17
	v_add_u32_e32 v175, 0, v16
	s_movk_i32 s10, 0x1400
	s_mov_b32 s11, 0xf800000
	s_mov_b32 s96, 0
	s_movk_i32 s100, 0x1400
	s_mov_b32 s101, 0
	s_branch .LBB0_355
